# RMSNorm phases: residual-stream x loads without the nt hint (x was just written by the preceding GEMM epilogue and is cache resident)
# speedup vs baseline: 1.0140x; 1.0033x over previous
.LBB0_256:
	s_andn2_b64 vcc, exec, s[0:1]
	s_cbranch_vccnz .LBB0_793
	s_cmp_gt_i32 s72, 6
	s_mov_b64 s[0:1], -1
	s_cbranch_scc0 .LBB0_264
	v_mov_b32_e32 v16, v224
	v_readlane_b32 s0, v251, 12
	v_ashrrev_i32_e32 v0, 6, v16
	s_nop 0
	v_add_u32_e32 v44, s0, v0
	s_movk_i32 s0, 0x3000
	v_cmp_gt_i32_e32 vcc, s0, v44
	s_and_saveexec_b64 s[4:5], vcc
	s_cbranch_execz .LBB0_263
	v_ashrrev_i32_e32 v45, 31, v44
	v_lshlrev_b32_e32 v2, 2, v16
	v_lshlrev_b64 v[0:1], 12, v[44:45]
	v_and_b32_e32 v18, 0xfc, v2
	v_lshl_add_u64 v[0:1], s[68:69], 0, v[0:1]
	v_lshlrev_b32_e32 v128, 2, v18
	v_lshl_add_u64 v[0:1], v[0:1], 0, v[128:129]
	global_load_dwordx4 v[12:15], v[0:1], off
	global_load_dwordx4 v[8:11], v[0:1], off offset:1024
	global_load_dwordx4 v[4:7], v[0:1], off offset:2048
	s_nop 0
	global_load_dwordx4 v[0:3], v[0:1], off offset:3072
	v_and_b32_e32 v17, 64, v226
	v_add_u32_e32 v17, 64, v17
	v_xor_b32_e32 v19, 32, v226
	v_cmp_lt_i32_e32 vcc, v19, v17
	s_load_dword s0, s[24:25], 0x0
	v_or_b32_e32 v20, 0x100, v18
	v_cndmask_b32_e32 v19, v226, v19, vcc
	v_lshlrev_b32_e32 v47, 2, v19
	v_xor_b32_e32 v19, 16, v226
	v_cmp_lt_i32_e32 vcc, v19, v17
	s_waitcnt lgkmcnt(0)
	s_lshl_b32 s36, s0, 3
	v_readlane_b32 s0, v254, 26
	v_cndmask_b32_e32 v19, v226, v19, vcc
	v_lshlrev_b32_e32 v48, 2, v19
	v_xor_b32_e32 v19, 8, v226
	v_cmp_lt_i32_e32 vcc, v19, v17
	v_readlane_b32 s1, v254, 27
	v_add_u32_e32 v26, s36, v44
	v_cndmask_b32_e32 v19, v226, v19, vcc
	v_lshlrev_b32_e32 v49, 2, v19
	v_xor_b32_e32 v19, 4, v226
	v_cmp_lt_i32_e32 vcc, v19, v17
	v_lshl_add_u64 v[32:33], s[0:1], 0, v[128:129]
	v_ashrrev_i32_e32 v27, 31, v26
	v_cndmask_b32_e32 v19, v226, v19, vcc
	v_lshlrev_b32_e32 v50, 2, v19
	v_xor_b32_e32 v19, 2, v226
	v_cmp_lt_i32_e32 vcc, v19, v17
	v_readlane_b32 s0, v253, 29
	v_lshlrev_b64 v[26:27], 12, v[26:27]
	v_cndmask_b32_e32 v19, v226, v19, vcc
	v_lshlrev_b32_e32 v51, 2, v19
	v_xor_b32_e32 v19, 1, v226
	v_cmp_lt_i32_e32 vcc, v19, v17
	s_add_u32 s0, s0, s30
	v_readlane_b32 s1, v253, 30
	v_cndmask_b32_e32 v17, v226, v19, vcc
	v_and_b32_e32 v19, 63, v16
	v_lshlrev_b32_e32 v52, 2, v17
	v_lshl_or_b32 v26, v19, 4, v26
	s_addc_u32 s1, s1, s31
	v_lshlrev_b64 v[16:17], 11, v[44:45]
	v_lshl_add_u64 v[34:35], s[0:1], 0, v[26:27]
	v_lshl_add_u64 v[16:17], s[74:75], 0, v[16:17]
	v_lshlrev_b32_e32 v128, 3, v19
	v_readlane_b32 s0, v253, 31
	v_or_b32_e32 v22, 0x200, v18
	v_or_b32_e32 v24, 0x300, v18
	s_ashr_i32 s37, s36, 31
	v_lshl_add_u64 v[16:17], v[16:17], 0, v[128:129]
	v_readlane_b32 s1, v253, 32
	s_lshl_b64 s[30:31], s[36:37], 12
	s_lshl_b64 s[38:39], s[36:37], 11
	v_lshl_add_u64 v[36:37], s[0:1], 0, v[16:17]
	s_mov_b64 s[40:41], 0
	v_lshlrev_b32_e32 v128, 2, v18
	v_lshlrev_b32_e32 v38, 2, v20
	v_lshlrev_b32_e32 v40, 2, v22
	v_lshlrev_b32_e32 v42, 2, v24
	s_waitcnt vmcnt(0)
	s_branch .LBB0_261

.LBB0_261:
	v_add_u32_e32 v45, s36, v44
	s_movk_i32 s0, 0x3000
	v_cmp_gt_i32_e64 s[0:1], s0, v45
	v_cmp_lt_i32_e32 vcc, s92, v45
	s_waitcnt vmcnt(4)
	v_mov_b32_e32 v16, v12
	v_mov_b32_e32 v17, v13
	v_mov_b32_e32 v18, v14
	v_mov_b32_e32 v19, v15
	v_mov_b32_e32 v20, v8
	v_mov_b32_e32 v21, v9
	v_mov_b32_e32 v22, v10
	v_mov_b32_e32 v23, v11
	v_mov_b32_e32 v24, v4
	v_mov_b32_e32 v25, v5
	v_mov_b32_e32 v26, v6
	v_mov_b32_e32 v27, v7
	v_mov_b32_e32 v28, v0
	v_mov_b32_e32 v29, v1
	v_mov_b32_e32 v30, v2
	v_mov_b32_e32 v31, v3
	s_and_saveexec_b64 s[6:7], s[0:1]
	s_cbranch_execz .LBB0_260
	global_load_dwordx4 v[16:19], v[34:35], off offset:-2048
	global_load_dwordx4 v[20:23], v[34:35], off offset:-1024
	global_load_dwordx4 v[24:27], v[34:35], off
	global_load_dwordx4 v[28:31], v[34:35], off offset:1024
	s_branch .LBB0_260

.LBB0_1662:
	v_lshlrev_b64 v[2:3], 12, v[2:3]
	v_lshl_add_u64 v[0:1], v[0:1], 0, v[2:3]
	v_lshlrev_b32_e32 v2, 2, v16
	v_and_b32_e32 v32, 0xfc, v2
	v_lshlrev_b32_e32 v128, 2, v32
	v_lshl_add_u64 v[0:1], v[0:1], 0, v[128:129]
	global_load_dwordx4 v[12:15], v[0:1], off
	global_load_dwordx4 v[8:11], v[0:1], off offset:1024
	global_load_dwordx4 v[4:7], v[0:1], off offset:2048
	s_nop 0
	global_load_dwordx4 v[0:3], v[0:1], off offset:3072
	v_and_b32_e32 v17, 64, v226
	v_add_u32_e32 v17, 64, v17
	v_xor_b32_e32 v18, 32, v226
	v_cmp_lt_i32_e32 vcc, v18, v17
	s_load_dword s4, s[24:25], 0x0
	v_readlane_b32 s6, v254, 46
	v_cndmask_b32_e32 v18, v226, v18, vcc
	v_lshlrev_b32_e32 v33, 2, v18
	v_xor_b32_e32 v18, 16, v226
	v_cmp_lt_i32_e32 vcc, v18, v17
	v_readlane_b32 s7, v254, 47
	v_lshlrev_b64 v[24:25], 11, v[36:37]
	v_cndmask_b32_e32 v18, v226, v18, vcc
	v_lshlrev_b32_e32 v50, 2, v18
	v_xor_b32_e32 v18, 8, v226
	v_cmp_lt_i32_e32 vcc, v18, v17
	v_and_b32_e32 v16, 63, v16
	s_waitcnt lgkmcnt(0)
	s_lshl_b32 s4, s4, 3
	v_cndmask_b32_e32 v18, v226, v18, vcc
	v_lshlrev_b32_e32 v51, 2, v18
	v_xor_b32_e32 v18, 4, v226
	v_cmp_lt_i32_e32 vcc, v18, v17
	v_lshl_add_u64 v[34:35], s[6:7], 0, v[128:129]
	v_lshl_add_u64 v[24:25], s[74:75], 0, v[24:25]
	v_cndmask_b32_e32 v18, v226, v18, vcc
	v_lshlrev_b32_e32 v52, 2, v18
	v_xor_b32_e32 v18, 2, v226
	v_cmp_lt_i32_e32 vcc, v18, v17
	v_lshlrev_b32_e32 v128, 3, v16
	v_readlane_b32 s6, v253, 31
	v_cndmask_b32_e32 v18, v226, v18, vcc
	v_lshlrev_b32_e32 v53, 2, v18
	v_xor_b32_e32 v18, 1, v226
	v_cmp_lt_i32_e32 vcc, v18, v17
	v_or_b32_e32 v20, 0x200, v32
	v_or_b32_e32 v22, 0x300, v32
	v_cndmask_b32_e32 v17, v226, v18, vcc
	v_lshlrev_b32_e32 v54, 2, v17
	v_or_b32_e32 v18, 0x100, v32
	v_add_u32_e32 v38, s4, v36
	s_ashr_i32 s5, s4, 31
	v_lshl_add_u64 v[16:17], v[24:25], 0, v[128:129]
	v_readlane_b32 s7, v253, 32
	v_ashrrev_i32_e32 v39, 31, v38
	s_lshl_b64 s[30:31], s[4:5], 11
	v_lshl_add_u64 v[40:41], s[6:7], 0, v[16:17]
	s_mov_b64 s[36:37], 0
	v_lshlrev_b32_e32 v42, 2, v18
	v_lshlrev_b32_e32 v44, 2, v20
	v_lshlrev_b32_e32 v46, 2, v22
	s_waitcnt vmcnt(0)
	s_branch .LBB0_1666

.LBB0_1664:
	v_lshlrev_b64 v[16:17], 12, v[16:17]
	v_lshl_add_u64 v[16:17], v[18:19], 0, v[16:17]
	v_lshlrev_b32_e32 v128, 2, v32
	v_lshl_add_u64 v[16:17], v[16:17], 0, v[128:129]
	global_load_dwordx4 v[28:31], v[16:17], off
	global_load_dwordx4 v[24:27], v[16:17], off offset:1024
	global_load_dwordx4 v[20:23], v[16:17], off offset:2048
	s_nop 0
	global_load_dwordx4 v[16:19], v[16:17], off offset:3072

.LBB0_1762:
	v_readlane_b32 s4, v251, 12
	v_ashrrev_i32_e32 v0, 6, v224
	s_movk_i32 s12, 0x3000
	v_add_u32_e32 v32, s4, v0
	s_mov_b64 s[2:3], 0
	v_cmp_gt_i32_e32 vcc, s12, v32
	s_and_saveexec_b64 s[4:5], vcc
	s_cbranch_execz .LBB0_1767
	v_readlane_b32 s8, v250, 1
	s_lshl_b64 s[4:5], s[0:1], 2
	v_readlane_b32 s10, v250, 3
	v_readlane_b32 s11, v250, 4
	s_add_u32 s0, s10, s4
	v_ashrrev_i32_e32 v33, 31, v32
	s_addc_u32 s1, s11, s5
	v_lshlrev_b64 v[16:17], 12, v[32:33]
	v_lshlrev_b32_e32 v2, 4, v224
	v_lshl_add_u64 v[0:1], s[0:1], 0, v[16:17]
	v_and_b32_e32 v18, 0x3f0, v2
	v_mov_b32_e32 v19, 0
	v_lshl_add_u64 v[20:21], v[0:1], 0, v[18:19]
	global_load_dwordx4 v[0:3], v[20:21], off
	global_load_dwordx4 v[4:7], v[20:21], off offset:1024
	global_load_dwordx4 v[8:11], v[20:21], off offset:2048
	global_load_dwordx4 v[12:15], v[20:21], off offset:3072
	v_and_b32_e32 v20, 64, v226
	v_add_u32_e32 v20, 64, v20
	v_xor_b32_e32 v21, 32, v226
	v_cmp_lt_i32_e32 vcc, v21, v20
	v_readlane_b32 s0, v251, 7
	v_readlane_b32 s1, v251, 8
	v_cndmask_b32_e32 v21, v226, v21, vcc
	v_lshlrev_b32_e32 v33, 2, v21
	v_xor_b32_e32 v21, 16, v226
	v_cmp_lt_i32_e32 vcc, v21, v20
	s_load_dword s0, s[0:1], 0x0
	v_or_b32_e32 v16, v16, v18
	v_cndmask_b32_e32 v21, v226, v21, vcc
	v_lshlrev_b32_e32 v40, 2, v21
	v_xor_b32_e32 v21, 8, v226
	v_cmp_lt_i32_e32 vcc, v21, v20
	s_waitcnt lgkmcnt(0)
	s_lshl_b32 s6, s0, 3
	v_lshl_add_u64 v[36:37], s[10:11], 0, v[16:17]
	v_cndmask_b32_e32 v21, v226, v21, vcc
	v_lshlrev_b32_e32 v41, 2, v21
	v_xor_b32_e32 v21, 4, v226
	v_cmp_lt_i32_e32 vcc, v21, v20
	v_add_u32_e32 v16, s6, v32
	v_ashrrev_i32_e32 v17, 31, v16
	v_cndmask_b32_e32 v21, v226, v21, vcc
	v_lshlrev_b32_e32 v42, 2, v21
	v_xor_b32_e32 v21, 2, v226
	v_cmp_lt_i32_e32 vcc, v21, v20
	v_lshlrev_b64 v[16:17], 12, v[16:17]
	v_readlane_b32 s9, v250, 2
	v_cndmask_b32_e32 v21, v226, v21, vcc
	v_lshlrev_b32_e32 v43, 2, v21
	v_xor_b32_e32 v21, 1, v226
	v_cmp_lt_i32_e32 vcc, v21, v20
	s_ashr_i32 s7, s6, 31
	v_or_b32_e32 v16, v16, v18
	v_cndmask_b32_e32 v20, v226, v21, vcc
	v_lshlrev_b32_e32 v44, 2, v20
	v_lshl_add_u64 v[34:35], s[8:9], 0, v[18:19]
	s_lshl_b64 s[8:9], s[6:7], 12
	v_lshl_add_u64 v[38:39], s[10:11], 0, v[16:17]
	s_movk_i32 s7, 0x2fff
	v_mov_b32_e32 v45, 0x358637bd
	s_mov_b32 s13, 0x800000
	s_branch .LBB0_1765

.LBB0_1765:
	v_add_u32_e32 v32, s6, v32
	v_cmp_gt_i32_e64 s[0:1], s12, v32
	v_cmp_lt_i32_e32 vcc, s7, v32
	s_waitcnt vmcnt(3)
	v_mov_b32_e32 v28, v0
	v_mov_b32_e32 v29, v1
	v_mov_b32_e32 v30, v2
	v_mov_b32_e32 v31, v3
	s_waitcnt vmcnt(2)
	v_mov_b32_e32 v16, v4
	v_mov_b32_e32 v17, v5
	v_mov_b32_e32 v18, v6
	v_mov_b32_e32 v19, v7
	s_waitcnt vmcnt(1)
	v_mov_b32_e32 v20, v8
	v_mov_b32_e32 v21, v9
	v_mov_b32_e32 v22, v10
	v_mov_b32_e32 v23, v11
	s_waitcnt vmcnt(0)
	v_mov_b32_e32 v24, v12
	v_mov_b32_e32 v25, v13
	v_mov_b32_e32 v26, v14
	v_mov_b32_e32 v27, v15
	s_and_saveexec_b64 s[10:11], s[0:1]
	s_cbranch_execz .LBB0_1764
	v_lshl_add_u64 v[46:47], v[38:39], 0, s[4:5]
	global_load_dwordx4 v[28:31], v[46:47], off
	global_load_dwordx4 v[16:19], v[46:47], off offset:1024
	global_load_dwordx4 v[20:23], v[46:47], off offset:2048
	global_load_dwordx4 v[24:27], v[46:47], off offset:3072
	s_branch .LBB0_1764
